# swiglu: gate/value halves of the bf16 w_ffn_in copies pre-scaled by log2e / ln2 in the prologue so the epilogue drops 64 scale multiplies per unit (exp2 of negated accumulator directly)
# baseline (speedup 1.0000x reference)
.LBB0_51:
	s_andn2_b64 vcc, exec, s[6:7]
	s_cbranch_vccnz .LBB0_55
	s_add_i32 s5, s81, 0xf500
	s_cmpk_gt_i32 s81, 0xaff
	s_cselect_b64 s[6:7], -1, 0
	s_and_b64 s[8:9], s[6:7], exec
	s_cselect_b32 s5, s5, s81
	s_mul_hi_i32 s42, s4, 0x1600000
	s_mul_i32 s43, s4, 0x1600000
	s_sext_i32_i16 s4, s5
	s_mulk_i32 s4, 0xba3
	s_cselect_b32 s9, s25, s17
	s_cselect_b32 s8, s24, s16
	s_lshr_b32 s28, s4, 31
	s_ashr_i32 s4, s4, 19
	s_add_i32 s4, s4, s28
	s_mul_i32 s28, s4, 0xb0
	s_sub_i32 s5, s5, s28
	s_sext_i32_i16 s36, s5
	s_lshl_b32 s28, s36, 5
	s_bitcmp0_b32 s5, 2
	s_cselect_b32 s5, 0, 0xb00
	s_mov_b32 s84, 0x3f317218
	s_cselect_b32 s84, 0x3fb8aa3b, s84
	s_lshl_b32 s36, s36, 4
	s_and_b32 s36, s36, 0xffffff80
	s_add_i32 s5, s5, s36
	s_and_b32 s36, s28, 0x60
	s_or_b32 s36, s5, s36
	s_ashr_i32 s37, s36, 31
	s_lshl_b32 s4, s4, 6
	v_lshl_add_u64 v[36:37], s[8:9], 0, v[14:15]
	s_lshl_b64 s[8:9], s[36:37], 2
	s_add_u32 s8, s8, s43
	s_addc_u32 s9, s9, s42
	v_mov_b64_e32 v[38:39], s[8:9]
	v_or_b32_e32 v10, s4, v63
	v_mad_i64_i32 v[30:31], s[8:9], v10, s58, v[38:39]
	v_or_b32_e32 v10, s4, v64
	v_mad_i64_i32 v[32:33], s[8:9], v10, s58, v[38:39]
	v_or_b32_e32 v10, s4, v65
	v_or_b32_e32 v2, s4, v59
	v_or_b32_e32 v4, s4, v60
	v_or_b32_e32 v6, s4, v61
	v_or_b32_e32 v8, s4, v62
	v_mad_i64_i32 v[34:35], s[8:9], v10, s58, v[38:39]
	v_or_b32_e32 v10, s4, v18
	v_mad_i64_i32 v[2:3], s[8:9], v2, s58, v[38:39]
	v_mad_i64_i32 v[4:5], s[8:9], v4, s58, v[38:39]
	v_mad_i64_i32 v[6:7], s[8:9], v6, s58, v[38:39]
	v_mad_i64_i32 v[8:9], s[8:9], v8, s58, v[38:39]
	v_mad_i64_i32 v[38:39], s[8:9], v10, s58, v[38:39]
	v_lshl_add_u64 v[2:3], v[36:37], 0, v[2:3]
	v_lshl_add_u64 v[4:5], v[36:37], 0, v[4:5]
	v_lshl_add_u64 v[6:7], v[36:37], 0, v[6:7]
	v_lshl_add_u64 v[8:9], v[36:37], 0, v[8:9]
	v_lshl_add_u64 v[30:31], v[36:37], 0, v[30:31]
	v_lshl_add_u64 v[32:33], v[36:37], 0, v[32:33]
	v_lshl_add_u64 v[34:35], v[36:37], 0, v[34:35]
	s_ashr_i32 s5, s4, 31
	v_lshl_add_u64 v[36:37], v[36:37], 0, v[38:39]
	s_mov_b64 s[8:9], 0
	v_mov_b32_e32 v10, v50
.LBB0_53:
	v_lshl_add_u64 v[38:39], v[36:37], 0, s[8:9]
	v_lshl_add_u64 v[40:41], v[34:35], 0, s[8:9]
	v_lshl_add_u64 v[80:81], v[32:33], 0, s[8:9]
	v_lshl_add_u64 v[82:83], v[30:31], 0, s[8:9]
	v_lshl_add_u64 v[84:85], v[8:9], 0, s[8:9]
	v_lshl_add_u64 v[86:87], v[6:7], 0, s[8:9]
	v_lshl_add_u64 v[88:89], v[4:5], 0, s[8:9]
	v_lshl_add_u64 v[90:91], v[2:3], 0, s[8:9]
	global_load_dword v148, v[38:39], off nt
	s_nop 0
	global_load_dword v149, v[40:41], off nt
	global_load_dword v150, v[80:81], off nt
	s_nop 0
	global_load_dword v151, v[82:83], off nt
	global_load_dword v152, v[84:85], off nt
	global_load_dword v153, v[86:87], off nt
	global_load_dword v154, v[88:89], off nt
	s_nop 0
	global_load_dword v155, v[90:91], off nt
	s_add_u32 s8, s8, 0x58000
	s_addc_u32 s9, s9, 0
	v_lshl_add_u64 v[38:39], v[36:37], 0, s[8:9]
	v_lshl_add_u64 v[40:41], v[34:35], 0, s[8:9]
	v_lshl_add_u64 v[80:81], v[32:33], 0, s[8:9]
	v_lshl_add_u64 v[82:83], v[30:31], 0, s[8:9]
	v_lshl_add_u64 v[84:85], v[8:9], 0, s[8:9]
	v_lshl_add_u64 v[86:87], v[6:7], 0, s[8:9]
	v_lshl_add_u64 v[88:89], v[4:5], 0, s[8:9]
	v_lshl_add_u64 v[90:91], v[2:3], 0, s[8:9]
	global_load_dword v156, v[38:39], off nt
	s_nop 0
	global_load_dword v157, v[40:41], off nt
	global_load_dword v158, v[80:81], off nt
	s_nop 0
	global_load_dword v159, v[82:83], off nt
	global_load_dword v160, v[84:85], off nt
	global_load_dword v161, v[86:87], off nt
	global_load_dword v162, v[88:89], off nt
	s_nop 0
	global_load_dword v163, v[90:91], off nt
	s_add_u32 s8, s8, 0x58000
	s_addc_u32 s9, s9, 0
	v_lshl_add_u64 v[38:39], v[36:37], 0, s[8:9]
	v_lshl_add_u64 v[40:41], v[34:35], 0, s[8:9]
	v_lshl_add_u64 v[80:81], v[32:33], 0, s[8:9]
	v_lshl_add_u64 v[82:83], v[30:31], 0, s[8:9]
	v_lshl_add_u64 v[84:85], v[8:9], 0, s[8:9]
	v_lshl_add_u64 v[86:87], v[6:7], 0, s[8:9]
	v_lshl_add_u64 v[88:89], v[4:5], 0, s[8:9]
	v_lshl_add_u64 v[90:91], v[2:3], 0, s[8:9]
	global_load_dword v164, v[38:39], off nt
	s_nop 0
	global_load_dword v165, v[40:41], off nt
	global_load_dword v166, v[80:81], off nt
	s_nop 0
	global_load_dword v167, v[82:83], off nt
	global_load_dword v168, v[84:85], off nt
	global_load_dword v169, v[86:87], off nt
	global_load_dword v170, v[88:89], off nt
	s_nop 0
	global_load_dword v171, v[90:91], off nt
	s_add_u32 s8, s8, 0x58000
	s_addc_u32 s9, s9, 0
	v_lshl_add_u64 v[38:39], v[36:37], 0, s[8:9]
	v_lshl_add_u64 v[40:41], v[34:35], 0, s[8:9]
	v_lshl_add_u64 v[80:81], v[32:33], 0, s[8:9]
	v_lshl_add_u64 v[82:83], v[30:31], 0, s[8:9]
	v_lshl_add_u64 v[84:85], v[8:9], 0, s[8:9]
	v_lshl_add_u64 v[86:87], v[6:7], 0, s[8:9]
	v_lshl_add_u64 v[88:89], v[4:5], 0, s[8:9]
	v_lshl_add_u64 v[90:91], v[2:3], 0, s[8:9]
	global_load_dword v172, v[38:39], off nt
	s_nop 0
	global_load_dword v173, v[40:41], off nt
	global_load_dword v174, v[80:81], off nt
	s_nop 0
	global_load_dword v175, v[82:83], off nt
	global_load_dword v176, v[84:85], off nt
	global_load_dword v177, v[86:87], off nt
	global_load_dword v178, v[88:89], off nt
	s_nop 0
	global_load_dword v179, v[90:91], off nt
	s_add_u32 s8, s8, 0x58000
	s_addc_u32 s9, s9, 0
	v_add_u32_e32 v83, 0x400, v10
	s_waitcnt vmcnt(30)
	ds_write2_b32 v10, v148, v149 offset1:66
	s_waitcnt vmcnt(28)
	ds_write2_b32 v10, v150, v151 offset0:132 offset1:198
	s_waitcnt vmcnt(26)
	ds_write2_b32 v83, v152, v153 offset0:8 offset1:74
	s_waitcnt vmcnt(24)
	ds_write2_b32 v83, v154, v155 offset0:140 offset1:206
	v_add_u32_e32 v10, 0x840, v10
	v_add_u32_e32 v83, 0x400, v10
	s_waitcnt vmcnt(22)
	ds_write2_b32 v10, v156, v157 offset1:66
	s_waitcnt vmcnt(20)
	ds_write2_b32 v10, v158, v159 offset0:132 offset1:198
	s_waitcnt vmcnt(18)
	ds_write2_b32 v83, v160, v161 offset0:8 offset1:74
	s_waitcnt vmcnt(16)
	ds_write2_b32 v83, v162, v163 offset0:140 offset1:206
	v_add_u32_e32 v10, 0x840, v10
	v_add_u32_e32 v83, 0x400, v10
	s_waitcnt vmcnt(14)
	ds_write2_b32 v10, v164, v165 offset1:66
	s_waitcnt vmcnt(12)
	ds_write2_b32 v10, v166, v167 offset0:132 offset1:198
	s_waitcnt vmcnt(10)
	ds_write2_b32 v83, v168, v169 offset0:8 offset1:74
	s_waitcnt vmcnt(8)
	ds_write2_b32 v83, v170, v171 offset0:140 offset1:206
	v_add_u32_e32 v10, 0x840, v10
	v_add_u32_e32 v83, 0x400, v10
	s_waitcnt vmcnt(6)
	ds_write2_b32 v10, v172, v173 offset1:66
	s_waitcnt vmcnt(4)
	ds_write2_b32 v10, v174, v175 offset0:132 offset1:198
	s_waitcnt vmcnt(2)
	ds_write2_b32 v83, v176, v177 offset0:8 offset1:74
	s_waitcnt vmcnt(0)
	ds_write2_b32 v83, v178, v179 offset0:140 offset1:206
	v_add_u32_e32 v10, 0x840, v10
	s_waitcnt lgkmcnt(0)
	ds_read2_b32 v[6:7], v45 offset1:8
	ds_read2_b32 v[30:31], v45 offset0:33 offset1:41
	ds_read2_b32 v[32:33], v45 offset0:66 offset1:74
	ds_read2_b32 v[34:35], v45 offset0:99 offset1:107
	ds_read2_b32 v[36:37], v45 offset0:132 offset1:140
	s_waitcnt lgkmcnt(4)
	v_mul_f32_e32 v6, s84, v6
	v_bfe_u32 v2, v6, 16, 1
	v_add3_u32 v2, v6, v2, s53
	s_waitcnt lgkmcnt(3)
	v_mul_f32_e32 v30, s84, v30
	v_bfe_u32 v3, v30, 16, 1
	v_lshrrev_b32_e32 v2, 16, v2
	v_add3_u32 v3, v30, v3, s53
	ds_read2_b32 v[38:39], v45 offset0:165 offset1:173
	v_and_or_b32 v2, v3, s54, v2
	s_waitcnt lgkmcnt(3)
	v_mul_f32_e32 v32, s84, v32
	v_bfe_u32 v3, v32, 16, 1
	v_add3_u32 v3, v32, v3, s53
	s_waitcnt lgkmcnt(2)
	v_mul_f32_e32 v34, s84, v34
	v_bfe_u32 v4, v34, 16, 1
	ds_read2_b32 v[40:41], v45 offset0:198 offset1:206
	s_and_b64 s[6:7], s[6:7], exec
	v_lshrrev_b32_e32 v3, 16, v3
	v_add3_u32 v4, v34, v4, s53
	ds_read2_b32 v[80:81], v45 offset0:231 offset1:239
	s_cselect_b32 s6, 0x1500000, 0
	v_and_or_b32 v3, v4, s54, v3
	s_waitcnt lgkmcnt(3)
	v_mul_f32_e32 v36, s84, v36
	v_bfe_u32 v4, v36, 16, 1
	s_add_u32 s6, s79, s6
	v_add3_u32 v4, v36, v4, s53
	s_waitcnt lgkmcnt(2)
	v_mul_f32_e32 v38, s84, v38
	v_bfe_u32 v5, v38, 16, 1
	s_addc_u32 s7, s80, 0
	s_lshl_b64 s[4:5], s[4:5], 1
	v_lshrrev_b32_e32 v4, 16, v4
	v_add3_u32 v5, v38, v5, s53
	s_add_u32 s4, s6, s4
	v_and_or_b32 v4, v5, s54, v4
	s_waitcnt lgkmcnt(1)
	v_mul_f32_e32 v40, s84, v40
	v_bfe_u32 v5, v40, 16, 1
	v_or_b32_e32 v82, s28, v44
	s_addc_u32 s5, s7, s5
	v_lshlrev_b32_e32 v10, 1, v12
	v_add3_u32 v5, v40, v5, s53
	s_waitcnt lgkmcnt(0)
	v_mul_f32_e32 v80, s84, v80
	v_bfe_u32 v6, v80, 16, 1
	v_ashrrev_i32_e32 v83, 31, v82
	v_lshl_add_u64 v[8:9], s[4:5], 0, v[10:11]
	v_lshrrev_b32_e32 v5, 16, v5
	v_add3_u32 v6, v80, v6, s53
	v_lshlrev_b64 v[82:83], 11, v[82:83]
	v_and_or_b32 v5, v6, s54, v5
	v_lshl_add_u64 v[82:83], v[8:9], 0, v[82:83]
	global_store_dwordx4 v[82:83], v[2:5], off
	v_mul_f32_e32 v81, s84, v81
	v_bfe_u32 v6, v81, 16, 1
	v_add3_u32 v6, v81, v6, s53
	v_mul_f32_e32 v7, s84, v7
	v_bfe_u32 v2, v7, 16, 1
	v_add3_u32 v2, v7, v2, s53
	v_mul_f32_e32 v31, s84, v31
	v_bfe_u32 v3, v31, 16, 1
	v_lshrrev_b32_e32 v2, 16, v2
	v_add3_u32 v3, v31, v3, s53
	v_and_or_b32 v2, v3, s54, v2
	v_mul_f32_e32 v33, s84, v33
	v_bfe_u32 v3, v33, 16, 1
	v_add3_u32 v3, v33, v3, s53
	v_mul_f32_e32 v35, s84, v35
	v_bfe_u32 v4, v35, 16, 1
	v_lshrrev_b32_e32 v3, 16, v3
	v_add3_u32 v4, v35, v4, s53
	v_and_or_b32 v3, v4, s54, v3
	v_mul_f32_e32 v37, s84, v37
	v_bfe_u32 v4, v37, 16, 1
	v_add3_u32 v4, v37, v4, s53
	v_mul_f32_e32 v39, s84, v39
	v_bfe_u32 v5, v39, 16, 1
	v_lshrrev_b32_e32 v4, 16, v4
	v_add3_u32 v5, v39, v5, s53
	v_and_or_b32 v4, v5, s54, v4
	v_mul_f32_e32 v41, s84, v41
	v_bfe_u32 v5, v41, 16, 1
	v_add3_u32 v5, v41, v5, s53
	v_lshrrev_b32_e32 v5, 16, v5
	v_and_or_b32 v5, v6, s54, v5
	v_or_b32_e32 v6, s28, v46
	v_ashrrev_i32_e32 v7, 31, v6
	v_lshlrev_b64 v[6:7], 11, v[6:7]
	ds_read2_b32 v[30:31], v45 offset0:16 offset1:24
	v_lshl_add_u64 v[6:7], v[8:9], 0, v[6:7]
	global_store_dwordx4 v[6:7], v[2:5], off
	ds_read2_b32 v[6:7], v45 offset0:49 offset1:57
	ds_read2_b32 v[32:33], v45 offset0:82 offset1:90
	ds_read2_b32 v[34:35], v45 offset0:115 offset1:123
	s_waitcnt lgkmcnt(3)
	v_mul_f32_e32 v30, s84, v30
	v_bfe_u32 v2, v30, 16, 1
	v_add3_u32 v2, v30, v2, s53
	s_waitcnt lgkmcnt(2)
	v_mul_f32_e32 v6, s84, v6
	v_bfe_u32 v3, v6, 16, 1
	ds_read2_b32 v[36:37], v45 offset0:148 offset1:156
	v_lshrrev_b32_e32 v2, 16, v2
	v_add3_u32 v3, v6, v3, s53
	ds_read2_b32 v[38:39], v45 offset0:181 offset1:189
	v_and_or_b32 v2, v3, s54, v2
	s_waitcnt lgkmcnt(3)
	v_mul_f32_e32 v32, s84, v32
	v_bfe_u32 v3, v32, 16, 1
	v_add3_u32 v3, v32, v3, s53
	s_waitcnt lgkmcnt(2)
	v_mul_f32_e32 v34, s84, v34
	v_bfe_u32 v4, v34, 16, 1
	ds_read2_b32 v[40:41], v45 offset0:214 offset1:222
	v_lshrrev_b32_e32 v3, 16, v3
	v_add3_u32 v4, v34, v4, s53
	ds_read2_b32 v[80:81], v45 offset0:247 offset1:255
	v_and_or_b32 v3, v4, s54, v3
	s_waitcnt lgkmcnt(3)
	v_mul_f32_e32 v36, s84, v36
	v_bfe_u32 v4, v36, 16, 1
	v_add3_u32 v4, v36, v4, s53
	s_waitcnt lgkmcnt(2)
	v_mul_f32_e32 v38, s84, v38
	v_bfe_u32 v5, v38, 16, 1
	v_lshrrev_b32_e32 v4, 16, v4
	v_add3_u32 v5, v38, v5, s53
	v_and_or_b32 v4, v5, s54, v4
	s_waitcnt lgkmcnt(1)
	v_mul_f32_e32 v40, s84, v40
	v_bfe_u32 v5, v40, 16, 1
	v_or_b32_e32 v82, s28, v47
	v_add3_u32 v5, v40, v5, s53
	s_waitcnt lgkmcnt(0)
	v_mul_f32_e32 v80, s84, v80
	v_bfe_u32 v6, v80, 16, 1
	v_ashrrev_i32_e32 v83, 31, v82
	v_lshrrev_b32_e32 v5, 16, v5
	v_add3_u32 v6, v80, v6, s53
	v_lshlrev_b64 v[82:83], 11, v[82:83]
	v_and_or_b32 v5, v6, s54, v5
	v_lshl_add_u64 v[82:83], v[8:9], 0, v[82:83]
	global_store_dwordx4 v[82:83], v[2:5], off
	v_mul_f32_e32 v81, s84, v81
	v_bfe_u32 v6, v81, 16, 1
	v_add3_u32 v6, v81, v6, s53
	v_mul_f32_e32 v31, s84, v31
	v_bfe_u32 v2, v31, 16, 1
	v_add3_u32 v2, v31, v2, s53
	v_mul_f32_e32 v7, s84, v7
	v_bfe_u32 v3, v7, 16, 1
	v_lshrrev_b32_e32 v2, 16, v2
	v_add3_u32 v3, v7, v3, s53
	v_and_or_b32 v2, v3, s54, v2
	v_mul_f32_e32 v33, s84, v33
	v_bfe_u32 v3, v33, 16, 1
	v_add3_u32 v3, v33, v3, s53
	v_mul_f32_e32 v35, s84, v35
	v_bfe_u32 v4, v35, 16, 1
	v_lshrrev_b32_e32 v3, 16, v3
	v_add3_u32 v4, v35, v4, s53
	v_and_or_b32 v3, v4, s54, v3
	v_mul_f32_e32 v37, s84, v37
	v_bfe_u32 v4, v37, 16, 1
	v_add3_u32 v4, v37, v4, s53
	v_mul_f32_e32 v39, s84, v39
	v_bfe_u32 v5, v39, 16, 1
	v_lshrrev_b32_e32 v4, 16, v4
	v_add3_u32 v5, v39, v5, s53
	v_and_or_b32 v4, v5, s54, v4
	v_mul_f32_e32 v41, s84, v41
	v_bfe_u32 v5, v41, 16, 1
	v_add3_u32 v5, v41, v5, s53
	v_lshrrev_b32_e32 v5, 16, v5
	v_and_or_b32 v5, v6, s54, v5
	v_or_b32_e32 v6, s28, v48
	v_ashrrev_i32_e32 v7, 31, v6
	v_lshlrev_b64 v[6:7], 11, v[6:7]
	v_lshl_add_u64 v[6:7], v[8:9], 0, v[6:7]
	global_store_dwordx4 v[6:7], v[2:5], off
	s_waitcnt lgkmcnt(0)

.LBB0_377:
	v_exp_f32_e64 v149, -v122
	v_pk_mul_f32 v[128:129], v[128:129], v[124:125]
	v_pk_mul_f32 v[120:121], v[120:121], v[116:117]
	v_pk_mul_f32 v[112:113], v[112:113], v[108:109]
	v_add_f32_e32 v149, 1.0, v149
	v_rcp_f32_e32 v152, v149
	v_exp_f32_e64 v149, -v123
	v_pk_mul_f32 v[122:123], v[126:127], v[122:123]
	v_pk_mul_f32 v[104:105], v[104:105], v[100:101]
	v_pk_mul_f32 v[96:97], v[96:97], v[92:93]
	v_add_f32_e32 v149, 1.0, v149
	v_rcp_f32_e32 v153, v149
	v_pk_mul_f32 v[88:89], v[88:89], v[84:85]
	v_pk_mul_f32 v[80:81], v[80:81], v[76:77]
	v_pk_mul_f32 v[72:73], v[72:73], v[68:69]
	v_pk_mul_f32 v[122:123], v[122:123], v[152:153]
	v_pk_mul_f32 v[64:65], v[64:65], v[60:61]
	v_cvt_pk_bf16_f32 v122, v122, v123
	v_exp_f32_e64 v123, -v124
	v_pk_mul_f32 v[56:57], v[56:57], v[52:53]
	v_pk_mul_f32 v[48:49], v[48:49], v[44:45]
	v_pk_mul_f32 v[40:41], v[40:41], v[36:37]
	v_add_f32_e32 v123, 1.0, v123
	v_rcp_f32_e32 v124, v123
	v_exp_f32_e64 v123, -v125
	v_pk_mul_f32 v[32:33], v[32:33], v[28:29]
	v_pk_mul_f32 v[24:25], v[24:25], v[20:21]
	v_pk_mul_f32 v[16:17], v[16:17], v[12:13]
	v_add_f32_e32 v123, 1.0, v123
	v_rcp_f32_e32 v125, v123
	v_pk_mul_f32 v[2:3], v[2:3], v[6:7]
	v_lshl_add_u32 v148, s26, 8, v144
	v_lshl_or_b32 v142, s24, 7, v146
	v_pk_mul_f32 v[124:125], v[128:129], v[124:125]
	v_ashrrev_i32_e32 v143, 31, v142
	v_cvt_pk_bf16_f32 v123, v124, v125
	v_exp_f32_e64 v124, -v114
	v_exp_f32_e64 v125, -v115
	v_pk_mul_f32 v[114:115], v[118:119], v[114:115]
	v_mov_b64_e32 v[140:141], s[6:7]
	v_add_f32_e32 v124, 1.0, v124
	v_add_f32_e32 v125, 1.0, v125
	v_rcp_f32_e32 v124, v124
	v_rcp_f32_e32 v125, v125
	v_pk_mul_f32 v[4:5], v[4:5], v[8:9]
	v_mad_i64_i32 v[150:151], s[24:25], v148, s86, v[140:141]
	v_pk_mul_f32 v[114:115], v[114:115], v[124:125]
	v_lshlrev_b64 v[142:143], 1, v[142:143]
	v_cvt_pk_bf16_f32 v124, v114, v115
	v_exp_f32_e64 v114, -v116
	v_exp_f32_e64 v115, -v117
	v_exp_f32_e64 v116, -v106
	v_exp_f32_e64 v117, -v107
	v_pk_mul_f32 v[106:107], v[110:111], v[106:107]
	v_add_f32_e32 v116, 1.0, v116
	v_add_f32_e32 v117, 1.0, v117
	v_rcp_f32_e32 v116, v116
	v_rcp_f32_e32 v117, v117
	v_add_f32_e32 v114, 1.0, v114
	v_rcp_f32_e32 v114, v114
	v_pk_mul_f32 v[106:107], v[106:107], v[116:117]
	v_add_f32_e32 v115, 1.0, v115
	v_cvt_pk_bf16_f32 v106, v106, v107
	v_exp_f32_e64 v107, -v108
	v_rcp_f32_e32 v115, v115
	v_lshl_add_u64 v[150:151], v[150:151], 0, v[142:143]
	s_andn2_b64 vcc, exec, s[18:19]
	v_add_f32_e32 v107, 1.0, v107
	v_rcp_f32_e32 v108, v107
	v_exp_f32_e64 v107, -v109
	v_pk_mul_f32 v[114:115], v[120:121], v[114:115]
	v_add_f32_e32 v107, 1.0, v107
	v_rcp_f32_e32 v109, v107
	v_cvt_pk_bf16_f32 v125, v114, v115
	v_or_b32_e32 v114, 16, v148
	v_mad_i64_i32 v[114:115], s[24:25], v114, s86, v[140:141]
	v_pk_mul_f32 v[108:109], v[112:113], v[108:109]
	v_lshl_add_u64 v[114:115], v[114:115], 0, v[142:143]
	v_cvt_pk_bf16_f32 v107, v108, v109
	v_exp_f32_e64 v108, -v98
	v_exp_f32_e64 v109, -v99
	v_pk_mul_f32 v[98:99], v[102:103], v[98:99]
	global_store_dwordx4 v[150:151], v[122:125], off sc1
	v_add_f32_e32 v108, 1.0, v108
	v_add_f32_e32 v109, 1.0, v109
	v_rcp_f32_e32 v108, v108
	v_rcp_f32_e32 v109, v109
	s_nop 0
	v_pk_mul_f32 v[98:99], v[98:99], v[108:109]
	s_nop 0
	v_cvt_pk_bf16_f32 v108, v98, v99
	v_exp_f32_e64 v98, -v100
	v_exp_f32_e64 v99, -v101
	v_exp_f32_e64 v100, -v90
	v_exp_f32_e64 v101, -v91
	v_pk_mul_f32 v[90:91], v[94:95], v[90:91]
	v_add_f32_e32 v100, 1.0, v100
	v_add_f32_e32 v101, 1.0, v101
	v_rcp_f32_e32 v100, v100
	v_rcp_f32_e32 v101, v101
	v_add_f32_e32 v98, 1.0, v98
	v_rcp_f32_e32 v98, v98
	v_pk_mul_f32 v[90:91], v[90:91], v[100:101]
	v_add_f32_e32 v99, 1.0, v99
	v_cvt_pk_bf16_f32 v90, v90, v91
	v_exp_f32_e64 v91, -v92
	v_rcp_f32_e32 v99, v99
	v_add_f32_e32 v91, 1.0, v91
	v_rcp_f32_e32 v92, v91
	v_exp_f32_e64 v91, -v93
	v_pk_mul_f32 v[98:99], v[104:105], v[98:99]
	v_add_f32_e32 v91, 1.0, v91
	v_rcp_f32_e32 v93, v91
	v_cvt_pk_bf16_f32 v109, v98, v99
	v_or_b32_e32 v98, 32, v148
	v_mad_i64_i32 v[98:99], s[24:25], v98, s86, v[140:141]
	v_pk_mul_f32 v[92:93], v[96:97], v[92:93]
	v_lshl_add_u64 v[98:99], v[98:99], 0, v[142:143]
	v_cvt_pk_bf16_f32 v91, v92, v93
	v_exp_f32_e64 v92, -v82
	v_exp_f32_e64 v93, -v83
	v_pk_mul_f32 v[82:83], v[86:87], v[82:83]
	global_store_dwordx4 v[114:115], v[106:109], off sc1
	v_add_f32_e32 v92, 1.0, v92
	v_add_f32_e32 v93, 1.0, v93
	v_rcp_f32_e32 v92, v92
	v_rcp_f32_e32 v93, v93
	s_nop 0
	v_pk_mul_f32 v[82:83], v[82:83], v[92:93]
	s_nop 0
	v_cvt_pk_bf16_f32 v92, v82, v83
	v_exp_f32_e64 v82, -v84
	v_exp_f32_e64 v83, -v85
	v_exp_f32_e64 v84, -v74
	v_exp_f32_e64 v85, -v75
	v_pk_mul_f32 v[74:75], v[78:79], v[74:75]
	v_add_f32_e32 v84, 1.0, v84
	v_add_f32_e32 v85, 1.0, v85
	v_rcp_f32_e32 v84, v84
	v_rcp_f32_e32 v85, v85
	v_add_f32_e32 v82, 1.0, v82
	v_rcp_f32_e32 v82, v82
	v_pk_mul_f32 v[74:75], v[74:75], v[84:85]
	v_add_f32_e32 v83, 1.0, v83
	v_cvt_pk_bf16_f32 v74, v74, v75
	v_exp_f32_e64 v75, -v76
	v_rcp_f32_e32 v83, v83
	v_add_f32_e32 v75, 1.0, v75
	v_rcp_f32_e32 v76, v75
	v_exp_f32_e64 v75, -v77
	v_pk_mul_f32 v[82:83], v[88:89], v[82:83]
	v_add_f32_e32 v75, 1.0, v75
	v_rcp_f32_e32 v77, v75
	v_cvt_pk_bf16_f32 v93, v82, v83
	v_or_b32_e32 v82, 48, v148
	v_mad_i64_i32 v[82:83], s[24:25], v82, s86, v[140:141]
	v_pk_mul_f32 v[76:77], v[80:81], v[76:77]
	v_lshl_add_u64 v[82:83], v[82:83], 0, v[142:143]
	v_cvt_pk_bf16_f32 v75, v76, v77
	v_exp_f32_e64 v76, -v66
	v_exp_f32_e64 v77, -v67
	v_pk_mul_f32 v[66:67], v[70:71], v[66:67]
	global_store_dwordx4 v[98:99], v[90:93], off sc1
	v_add_f32_e32 v76, 1.0, v76
	v_add_f32_e32 v77, 1.0, v77
	v_rcp_f32_e32 v76, v76
	v_rcp_f32_e32 v77, v77
	s_nop 0
	v_pk_mul_f32 v[66:67], v[66:67], v[76:77]
	s_nop 0
	v_cvt_pk_bf16_f32 v76, v66, v67
	v_exp_f32_e64 v66, -v68
	v_exp_f32_e64 v67, -v69
	v_exp_f32_e64 v68, -v58
	v_exp_f32_e64 v69, -v59
	v_pk_mul_f32 v[58:59], v[62:63], v[58:59]
	v_add_f32_e32 v68, 1.0, v68
	v_add_f32_e32 v69, 1.0, v69
	v_rcp_f32_e32 v68, v68
	v_rcp_f32_e32 v69, v69
	v_add_f32_e32 v66, 1.0, v66
	v_rcp_f32_e32 v66, v66
	v_pk_mul_f32 v[58:59], v[58:59], v[68:69]
	v_add_f32_e32 v67, 1.0, v67
	v_cvt_pk_bf16_f32 v58, v58, v59
	v_exp_f32_e64 v59, -v60
	v_rcp_f32_e32 v67, v67
	v_add_f32_e32 v59, 1.0, v59
	v_rcp_f32_e32 v60, v59
	v_exp_f32_e64 v59, -v61
	v_pk_mul_f32 v[66:67], v[72:73], v[66:67]
	v_add_f32_e32 v59, 1.0, v59
	v_rcp_f32_e32 v61, v59
	v_cvt_pk_bf16_f32 v77, v66, v67
	v_add_u32_e32 v66, 0x80, v148
	v_mad_i64_i32 v[66:67], s[24:25], v66, s86, v[140:141]
	v_pk_mul_f32 v[60:61], v[64:65], v[60:61]
	v_lshl_add_u64 v[66:67], v[66:67], 0, v[142:143]
	v_cvt_pk_bf16_f32 v59, v60, v61
	v_exp_f32_e64 v60, -v50
	v_exp_f32_e64 v61, -v51
	v_pk_mul_f32 v[50:51], v[54:55], v[50:51]
	global_store_dwordx4 v[82:83], v[74:77], off sc1
	v_add_f32_e32 v60, 1.0, v60
	v_add_f32_e32 v61, 1.0, v61
	v_rcp_f32_e32 v60, v60
	v_rcp_f32_e32 v61, v61
	s_nop 0
	v_pk_mul_f32 v[50:51], v[50:51], v[60:61]
	s_nop 0
	v_cvt_pk_bf16_f32 v60, v50, v51
	v_exp_f32_e64 v50, -v52
	v_exp_f32_e64 v51, -v53
	v_exp_f32_e64 v52, -v42
	v_exp_f32_e64 v53, -v43
	v_pk_mul_f32 v[42:43], v[46:47], v[42:43]
	v_add_f32_e32 v52, 1.0, v52
	v_add_f32_e32 v53, 1.0, v53
	v_rcp_f32_e32 v52, v52
	v_rcp_f32_e32 v53, v53
	v_add_f32_e32 v50, 1.0, v50
	v_rcp_f32_e32 v50, v50
	v_pk_mul_f32 v[42:43], v[42:43], v[52:53]
	v_add_f32_e32 v51, 1.0, v51
	v_cvt_pk_bf16_f32 v42, v42, v43
	v_exp_f32_e64 v43, -v44
	v_rcp_f32_e32 v51, v51
	v_add_f32_e32 v43, 1.0, v43
	v_rcp_f32_e32 v44, v43
	v_exp_f32_e64 v43, -v45
	v_pk_mul_f32 v[50:51], v[56:57], v[50:51]
	v_add_f32_e32 v43, 1.0, v43
	v_rcp_f32_e32 v45, v43
	v_cvt_pk_bf16_f32 v61, v50, v51
	v_add_u32_e32 v50, 0x90, v148
	v_mad_i64_i32 v[50:51], s[24:25], v50, s86, v[140:141]
	v_pk_mul_f32 v[44:45], v[48:49], v[44:45]
	v_lshl_add_u64 v[50:51], v[50:51], 0, v[142:143]
	v_cvt_pk_bf16_f32 v43, v44, v45
	v_exp_f32_e64 v44, -v34
	v_exp_f32_e64 v45, -v35
	v_pk_mul_f32 v[34:35], v[38:39], v[34:35]
	global_store_dwordx4 v[66:67], v[58:61], off sc1
	v_add_f32_e32 v44, 1.0, v44
	v_add_f32_e32 v45, 1.0, v45
	v_rcp_f32_e32 v44, v44
	v_rcp_f32_e32 v45, v45
	s_nop 0
	v_pk_mul_f32 v[34:35], v[34:35], v[44:45]
	s_nop 0
	v_cvt_pk_bf16_f32 v44, v34, v35
	v_exp_f32_e64 v34, -v36
	v_exp_f32_e64 v35, -v37
	v_exp_f32_e64 v36, -v26
	v_exp_f32_e64 v37, -v27
	v_pk_mul_f32 v[26:27], v[30:31], v[26:27]
	v_add_f32_e32 v36, 1.0, v36
	v_add_f32_e32 v37, 1.0, v37
	v_rcp_f32_e32 v36, v36
	v_rcp_f32_e32 v37, v37
	v_add_f32_e32 v34, 1.0, v34
	v_rcp_f32_e32 v34, v34
	v_pk_mul_f32 v[26:27], v[26:27], v[36:37]
	v_add_f32_e32 v35, 1.0, v35
	v_cvt_pk_bf16_f32 v26, v26, v27
	v_exp_f32_e64 v27, -v28
	v_rcp_f32_e32 v35, v35
	v_add_f32_e32 v27, 1.0, v27
	v_rcp_f32_e32 v28, v27
	v_exp_f32_e64 v27, -v29
	v_pk_mul_f32 v[34:35], v[40:41], v[34:35]
	v_add_f32_e32 v27, 1.0, v27
	v_rcp_f32_e32 v29, v27
	v_cvt_pk_bf16_f32 v45, v34, v35
	v_add_u32_e32 v34, 0xa0, v148
	v_mad_i64_i32 v[34:35], s[24:25], v34, s86, v[140:141]
	v_pk_mul_f32 v[28:29], v[32:33], v[28:29]
	v_lshl_add_u64 v[34:35], v[34:35], 0, v[142:143]
	v_cvt_pk_bf16_f32 v27, v28, v29
	v_exp_f32_e64 v28, -v18
	v_exp_f32_e64 v29, -v19
	v_pk_mul_f32 v[18:19], v[22:23], v[18:19]
	global_store_dwordx4 v[50:51], v[42:45], off sc1
	v_add_f32_e32 v28, 1.0, v28
	v_add_f32_e32 v29, 1.0, v29
	v_rcp_f32_e32 v28, v28
	v_rcp_f32_e32 v29, v29
	s_nop 0
	v_pk_mul_f32 v[18:19], v[18:19], v[28:29]
	s_nop 0
	v_cvt_pk_bf16_f32 v28, v18, v19
	v_exp_f32_e64 v18, -v20
	v_exp_f32_e64 v19, -v21
	v_exp_f32_e64 v20, -v10
	v_exp_f32_e64 v21, -v11
	v_pk_mul_f32 v[10:11], v[14:15], v[10:11]
	v_add_f32_e32 v20, 1.0, v20
	v_add_f32_e32 v21, 1.0, v21
	v_rcp_f32_e32 v20, v20
	v_rcp_f32_e32 v21, v21
	v_add_f32_e32 v18, 1.0, v18
	v_rcp_f32_e32 v18, v18
	v_pk_mul_f32 v[10:11], v[10:11], v[20:21]
	v_add_f32_e32 v19, 1.0, v19
	v_cvt_pk_bf16_f32 v10, v10, v11
	v_exp_f32_e64 v11, -v12
	v_rcp_f32_e32 v19, v19
	v_add_f32_e32 v11, 1.0, v11
	v_rcp_f32_e32 v12, v11
	v_exp_f32_e64 v11, -v13
	v_pk_mul_f32 v[18:19], v[24:25], v[18:19]
	v_add_f32_e32 v11, 1.0, v11
	v_rcp_f32_e32 v13, v11
	v_cvt_pk_bf16_f32 v29, v18, v19
	v_add_u32_e32 v18, 0xb0, v148
	v_mad_i64_i32 v[18:19], s[24:25], v18, s86, v[140:141]
	v_pk_mul_f32 v[12:13], v[16:17], v[12:13]
	v_lshl_add_u64 v[18:19], v[18:19], 0, v[142:143]
	v_cvt_pk_bf16_f32 v11, v12, v13
	v_exp_f32_e64 v12, -v6
	v_exp_f32_e64 v13, -v7
	s_mov_b64 s[24:25], -1
	global_store_dwordx4 v[34:35], v[26:29], off sc1
	v_add_f32_e32 v12, 1.0, v12
	v_add_f32_e32 v13, 1.0, v13
	v_rcp_f32_e32 v12, v12
	v_rcp_f32_e32 v13, v13
	s_nop 0
	v_pk_mul_f32 v[2:3], v[2:3], v[12:13]
	s_nop 0
	v_cvt_pk_bf16_f32 v12, v2, v3
	v_exp_f32_e64 v2, -v8
	v_exp_f32_e64 v3, -v9
	v_add_f32_e32 v2, 1.0, v2
	v_add_f32_e32 v3, 1.0, v3
	v_rcp_f32_e32 v2, v2
	v_rcp_f32_e32 v3, v3
	s_nop 0
	v_pk_mul_f32 v[2:3], v[4:5], v[2:3]
	s_nop 0
	v_cvt_pk_bf16_f32 v13, v2, v3
	global_store_dwordx4 v[18:19], v[10:13], off sc1
	s_cbranch_vccnz .LBB0_367
	s_andn2_b64 vcc, exec, s[4:5]
	s_cbranch_vccnz .LBB0_366
	s_barrier
	s_branch .LBB0_366
